# grid barrier: non-leader workgroups poll the top-level generation word directly (one hop fewer); per-XCD generation publish removed
# speedup vs baseline: 1.0680x; 1.0041x over previous
.LBB0_117:
	s_or_b64 exec, exec, s[6:7]
	s_ashr_i32 s9, s8, 31
	s_lshl_b64 s[6:7], s[8:9], 10
	s_lshl_b32 s28, s20, 7
	s_or_b32 s6, s6, s28
	s_lshl_b64 s[6:7], s[6:7], 2
	s_add_u32 s50, s10, s6
	s_addc_u32 s51, s11, s7
	s_lshl_b64 s[8:9], s[8:9], 23
	s_lshl_b32 s28, s20, 9
	s_add_u32 s40, s44, s8
	s_addc_u32 s41, s45, s9
	s_add_u32 s52, s40, s28
	v_and_b32_e32 v11, 63, v32
	s_waitcnt vmcnt(0)
	v_ashrrev_i32_e32 v37, 5, v32
	s_addc_u32 s53, s41, 0
	s_add_i32 s40, 0, 0x600
	v_and_b32_e32 v35, 31, v32
	v_lshlrev_b32_e32 v12, 2, v11
	v_lshl_add_u32 v39, v37, 2, s40
	v_lshlrev_b32_e32 v0, 2, v35
	v_lshl_add_u32 v13, v35, 4, 0
	v_xor_b32_e32 v10, 64, v12
	v_xor_b32_e32 v9, 32, v12
	v_xor_b32_e32 v8, 16, v12
	v_xor_b32_e32 v3, 8, v12
	v_xor_b32_e32 v1, 4, v12
	s_mov_b32 s30, 0
	v_cmp_eq_u32_e32 vcc, 0, v35
	v_mov_b32_e32 v14, v39
	s_waitcnt lgkmcnt(0)
	s_barrier
	v_mov_b32_e32 v170, v13
	v_mov_b32_e32 v171, 0
	v_lshl_add_u64 v[182:183], s[50:51], 0, v[170:171]
	v_add_u32_e32 v186, 0, v37
	v_mul_hi_i32 v187, v186, s13
	v_lshrrev_b32_e32 v188, 31, v187
	v_ashrrev_i32_e32 v187, 3, v187
	v_add_u32_e32 v187, v187, v188
	v_mad_i32_i24 v188, v187, s16, v186
	v_lshl_add_u32 v144, v187, 9, v13
	v_cmp_eq_u32_e64 s[42:43], 1, v187
	v_cmp_eq_u32_e64 s[56:57], 0, v187
	s_nop 1
	v_cndmask_b32_e64 v189, -16, -4, s[42:43]
	v_cndmask_b32_e64 v189, v189, -1, s[56:57]
	v_mad_i32_i24 v189, v189, v188, v174
	v_cmp_eq_u32_e64 s[42:43], 0, v188
	v_lshlrev_b32_e32 v184, 12, v189
	v_add_u32_e32 v184, v184, v13
	v_mov_b32_e32 v185, 0
	v_lshl_add_u64 v[184:185], s[52:53], 0, v[184:185]
	v_cndmask_b32_e64 v184, v184, v182, s[42:43]
	v_cndmask_b32_e64 v185, v185, v183, s[42:43]
	global_load_dwordx4 v[44:47], v[184:185], off
	v_add_u32_e32 v186, 16, v37
	v_mul_hi_i32 v187, v186, s13
	v_lshrrev_b32_e32 v188, 31, v187
	v_ashrrev_i32_e32 v187, 3, v187
	v_add_u32_e32 v187, v187, v188
	v_mad_i32_i24 v188, v187, s16, v186
	v_lshl_add_u32 v145, v187, 9, v13
	v_cmp_eq_u32_e64 s[42:43], 1, v187
	v_cmp_eq_u32_e64 s[56:57], 0, v187
	s_nop 1
	v_cndmask_b32_e64 v189, -16, -4, s[42:43]
	v_cndmask_b32_e64 v189, v189, -1, s[56:57]
	v_mad_i32_i24 v189, v189, v188, v174
	v_cmp_eq_u32_e64 s[42:43], 0, v188
	v_lshlrev_b32_e32 v184, 12, v189
	v_add_u32_e32 v184, v184, v13
	v_mov_b32_e32 v185, 0
	v_lshl_add_u64 v[184:185], s[52:53], 0, v[184:185]
	v_cndmask_b32_e64 v184, v184, v182, s[42:43]
	v_cndmask_b32_e64 v185, v185, v183, s[42:43]
	global_load_dwordx4 v[48:51], v[184:185], off
	v_add_u32_e32 v186, 32, v37
	v_mul_hi_i32 v187, v186, s13
	v_lshrrev_b32_e32 v188, 31, v187
	v_ashrrev_i32_e32 v187, 3, v187
	v_add_u32_e32 v187, v187, v188
	v_mad_i32_i24 v188, v187, s16, v186
	v_lshl_add_u32 v146, v187, 9, v13
	v_cmp_eq_u32_e64 s[42:43], 1, v187
	v_cmp_eq_u32_e64 s[56:57], 0, v187
	s_nop 1
	v_cndmask_b32_e64 v189, -16, -4, s[42:43]
	v_cndmask_b32_e64 v189, v189, -1, s[56:57]
	v_mad_i32_i24 v189, v189, v188, v174
	v_cmp_eq_u32_e64 s[42:43], 0, v188
	v_lshlrev_b32_e32 v184, 12, v189
	v_add_u32_e32 v184, v184, v13
	v_mov_b32_e32 v185, 0
	v_lshl_add_u64 v[184:185], s[52:53], 0, v[184:185]
	v_cndmask_b32_e64 v184, v184, v182, s[42:43]
	v_cndmask_b32_e64 v185, v185, v183, s[42:43]
	global_load_dwordx4 v[52:55], v[184:185], off
	v_add_u32_e32 v186, 48, v37
	v_mul_hi_i32 v187, v186, s13
	v_lshrrev_b32_e32 v188, 31, v187
	v_ashrrev_i32_e32 v187, 3, v187
	v_add_u32_e32 v187, v187, v188
	v_mad_i32_i24 v188, v187, s16, v186
	v_lshl_add_u32 v147, v187, 9, v13
	v_cmp_eq_u32_e64 s[42:43], 1, v187
	v_cmp_eq_u32_e64 s[56:57], 0, v187
	s_nop 1
	v_cndmask_b32_e64 v189, -16, -4, s[42:43]
	v_cndmask_b32_e64 v189, v189, -1, s[56:57]
	v_mad_i32_i24 v189, v189, v188, v174
	v_cmp_eq_u32_e64 s[42:43], 0, v188
	v_lshlrev_b32_e32 v184, 12, v189
	v_add_u32_e32 v184, v184, v13
	v_mov_b32_e32 v185, 0
	v_lshl_add_u64 v[184:185], s[52:53], 0, v[184:185]
	v_cndmask_b32_e64 v184, v184, v182, s[42:43]
	v_cndmask_b32_e64 v185, v185, v183, s[42:43]
	global_load_dwordx4 v[56:59], v[184:185], off
	v_add_u32_e32 v186, 64, v37
	v_mul_hi_i32 v187, v186, s13
	v_lshrrev_b32_e32 v188, 31, v187
	v_ashrrev_i32_e32 v187, 3, v187
	v_add_u32_e32 v187, v187, v188
	v_mad_i32_i24 v188, v187, s16, v186
	v_lshl_add_u32 v148, v187, 9, v13
	v_cmp_eq_u32_e64 s[42:43], 1, v187
	v_cmp_eq_u32_e64 s[56:57], 0, v187
	s_nop 1
	v_cndmask_b32_e64 v189, -16, -4, s[42:43]
	v_cndmask_b32_e64 v189, v189, -1, s[56:57]
	v_mad_i32_i24 v189, v189, v188, v174
	v_cmp_eq_u32_e64 s[42:43], 0, v188
	v_lshlrev_b32_e32 v184, 12, v189
	v_add_u32_e32 v184, v184, v13
	v_mov_b32_e32 v185, 0
	v_lshl_add_u64 v[184:185], s[52:53], 0, v[184:185]
	v_cndmask_b32_e64 v184, v184, v182, s[42:43]
	v_cndmask_b32_e64 v185, v185, v183, s[42:43]
	global_load_dwordx4 v[60:63], v[184:185], off
	v_add_u32_e32 v186, 0x50, v37
	v_mul_hi_i32 v187, v186, s13
	v_lshrrev_b32_e32 v188, 31, v187
	v_ashrrev_i32_e32 v187, 3, v187
	v_add_u32_e32 v187, v187, v188
	v_mad_i32_i24 v188, v187, s16, v186
	v_lshl_add_u32 v149, v187, 9, v13
	v_cmp_eq_u32_e64 s[42:43], 1, v187
	v_cmp_eq_u32_e64 s[56:57], 0, v187
	s_nop 1
	v_cndmask_b32_e64 v189, -16, -4, s[42:43]
	v_cndmask_b32_e64 v189, v189, -1, s[56:57]
	v_mad_i32_i24 v189, v189, v188, v174
	v_cmp_eq_u32_e64 s[42:43], 0, v188
	v_lshlrev_b32_e32 v184, 12, v189
	v_add_u32_e32 v184, v184, v13
	v_mov_b32_e32 v185, 0
	v_lshl_add_u64 v[184:185], s[52:53], 0, v[184:185]
	v_cndmask_b32_e64 v184, v184, v182, s[42:43]
	v_cndmask_b32_e64 v185, v185, v183, s[42:43]
	global_load_dwordx4 v[64:67], v[184:185], off
	v_add_u32_e32 v186, 0x60, v37
	v_mul_hi_i32 v187, v186, s13
	v_lshrrev_b32_e32 v188, 31, v187
	v_ashrrev_i32_e32 v187, 3, v187
	v_add_u32_e32 v187, v187, v188
	v_mad_i32_i24 v188, v187, s16, v186
	v_lshl_add_u32 v150, v187, 9, v13
	v_cmp_eq_u32_e64 s[42:43], 1, v187
	v_cmp_eq_u32_e64 s[56:57], 0, v187
	s_nop 1
	v_cndmask_b32_e64 v189, -16, -4, s[42:43]
	v_cndmask_b32_e64 v189, v189, -1, s[56:57]
	v_mad_i32_i24 v189, v189, v188, v174
	v_cmp_eq_u32_e64 s[42:43], 0, v188
	v_lshlrev_b32_e32 v184, 12, v189
	v_add_u32_e32 v184, v184, v13
	v_mov_b32_e32 v185, 0
	v_lshl_add_u64 v[184:185], s[52:53], 0, v[184:185]
	v_cndmask_b32_e64 v184, v184, v182, s[42:43]
	v_cndmask_b32_e64 v185, v185, v183, s[42:43]
	global_load_dwordx4 v[68:71], v[184:185], off
	v_add_u32_e32 v186, 0x70, v37
	v_mul_hi_i32 v187, v186, s13
	v_lshrrev_b32_e32 v188, 31, v187
	v_ashrrev_i32_e32 v187, 3, v187
	v_add_u32_e32 v187, v187, v188
	v_mad_i32_i24 v188, v187, s16, v186
	v_lshl_add_u32 v151, v187, 9, v13
	v_cmp_eq_u32_e64 s[42:43], 1, v187
	v_cmp_eq_u32_e64 s[56:57], 0, v187
	s_nop 1
	v_cndmask_b32_e64 v189, -16, -4, s[42:43]
	v_cndmask_b32_e64 v189, v189, -1, s[56:57]
	v_mad_i32_i24 v189, v189, v188, v174
	v_cmp_eq_u32_e64 s[42:43], 0, v188
	v_lshlrev_b32_e32 v184, 12, v189
	v_add_u32_e32 v184, v184, v13
	v_mov_b32_e32 v185, 0
	v_lshl_add_u64 v[184:185], s[52:53], 0, v[184:185]
	v_cndmask_b32_e64 v184, v184, v182, s[42:43]
	v_cndmask_b32_e64 v185, v185, v183, s[42:43]
	global_load_dwordx4 v[72:75], v[184:185], off
	v_add_u32_e32 v186, 0x80, v37
	v_mul_hi_i32 v187, v186, s13
	v_lshrrev_b32_e32 v188, 31, v187
	v_ashrrev_i32_e32 v187, 3, v187
	v_add_u32_e32 v187, v187, v188
	v_mad_i32_i24 v188, v187, s16, v186
	v_lshl_add_u32 v152, v187, 9, v13
	v_cmp_eq_u32_e64 s[42:43], 1, v187
	v_cmp_eq_u32_e64 s[56:57], 0, v187
	s_nop 1
	v_cndmask_b32_e64 v189, -16, -4, s[42:43]
	v_cndmask_b32_e64 v189, v189, -1, s[56:57]
	v_mad_i32_i24 v189, v189, v188, v174
	v_cmp_eq_u32_e64 s[42:43], 0, v188
	v_lshlrev_b32_e32 v184, 12, v189
	v_add_u32_e32 v184, v184, v13
	v_mov_b32_e32 v185, 0
	v_lshl_add_u64 v[184:185], s[52:53], 0, v[184:185]
	v_cndmask_b32_e64 v184, v184, v182, s[42:43]
	v_cndmask_b32_e64 v185, v185, v183, s[42:43]
	global_load_dwordx4 v[76:79], v[184:185], off
	v_add_u32_e32 v186, 0x90, v37
	v_mul_hi_i32 v187, v186, s13
	v_lshrrev_b32_e32 v188, 31, v187
	v_ashrrev_i32_e32 v187, 3, v187
	v_add_u32_e32 v187, v187, v188
	v_mad_i32_i24 v188, v187, s16, v186
	v_lshl_add_u32 v153, v187, 9, v13
	v_cmp_eq_u32_e64 s[42:43], 1, v187
	v_cmp_eq_u32_e64 s[56:57], 0, v187
	s_nop 1
	v_cndmask_b32_e64 v189, -16, -4, s[42:43]
	v_cndmask_b32_e64 v189, v189, -1, s[56:57]
	v_mad_i32_i24 v189, v189, v188, v174
	v_cmp_eq_u32_e64 s[42:43], 0, v188
	v_lshlrev_b32_e32 v184, 12, v189
	v_add_u32_e32 v184, v184, v13
	v_mov_b32_e32 v185, 0
	v_lshl_add_u64 v[184:185], s[52:53], 0, v[184:185]
	v_cndmask_b32_e64 v184, v184, v182, s[42:43]
	v_cndmask_b32_e64 v185, v185, v183, s[42:43]
	global_load_dwordx4 v[80:83], v[184:185], off
	v_add_u32_e32 v186, 0xa0, v37
	v_mul_hi_i32 v187, v186, s13
	v_lshrrev_b32_e32 v188, 31, v187
	v_ashrrev_i32_e32 v187, 3, v187
	v_add_u32_e32 v187, v187, v188
	v_mad_i32_i24 v188, v187, s16, v186
	v_lshl_add_u32 v154, v187, 9, v13
	v_cmp_eq_u32_e64 s[42:43], 1, v187
	v_cmp_eq_u32_e64 s[56:57], 0, v187
	s_nop 1
	v_cndmask_b32_e64 v189, -16, -4, s[42:43]
	v_cndmask_b32_e64 v189, v189, -1, s[56:57]
	v_mad_i32_i24 v189, v189, v188, v174
	v_cmp_eq_u32_e64 s[42:43], 0, v188
	v_lshlrev_b32_e32 v184, 12, v189
	v_add_u32_e32 v184, v184, v13
	v_mov_b32_e32 v185, 0
	v_lshl_add_u64 v[184:185], s[52:53], 0, v[184:185]
	v_cndmask_b32_e64 v184, v184, v182, s[42:43]
	v_cndmask_b32_e64 v185, v185, v183, s[42:43]
	global_load_dwordx4 v[84:87], v[184:185], off
	v_add_u32_e32 v186, 0xb0, v37
	v_mul_hi_i32 v187, v186, s13
	v_lshrrev_b32_e32 v188, 31, v187
	v_ashrrev_i32_e32 v187, 3, v187
	v_add_u32_e32 v187, v187, v188
	v_mad_i32_i24 v188, v187, s16, v186
	v_lshl_add_u32 v155, v187, 9, v13
	v_cmp_eq_u32_e64 s[42:43], 1, v187
	v_cmp_eq_u32_e64 s[56:57], 0, v187
	s_nop 1
	v_cndmask_b32_e64 v189, -16, -4, s[42:43]
	v_cndmask_b32_e64 v189, v189, -1, s[56:57]
	v_mad_i32_i24 v189, v189, v188, v174
	v_cmp_eq_u32_e64 s[42:43], 0, v188
	v_lshlrev_b32_e32 v184, 12, v189
	v_add_u32_e32 v184, v184, v13
	v_mov_b32_e32 v185, 0
	v_lshl_add_u64 v[184:185], s[52:53], 0, v[184:185]
	v_cndmask_b32_e64 v184, v184, v182, s[42:43]
	v_cndmask_b32_e64 v185, v185, v183, s[42:43]
	global_load_dwordx4 v[88:91], v[184:185], off
	v_add_u32_e32 v186, 0xc0, v37
	v_mul_hi_i32 v187, v186, s13
	v_lshrrev_b32_e32 v188, 31, v187
	v_ashrrev_i32_e32 v187, 3, v187
	v_add_u32_e32 v187, v187, v188
	v_mad_i32_i24 v188, v187, s16, v186
	v_lshl_add_u32 v156, v187, 9, v13
	v_cmp_eq_u32_e64 s[42:43], 1, v187
	v_cmp_eq_u32_e64 s[56:57], 0, v187
	s_nop 1
	v_cndmask_b32_e64 v189, -16, -4, s[42:43]
	v_cndmask_b32_e64 v189, v189, -1, s[56:57]
	v_mad_i32_i24 v189, v189, v188, v174
	v_cmp_eq_u32_e64 s[42:43], 0, v188
	v_lshlrev_b32_e32 v184, 12, v189
	v_add_u32_e32 v184, v184, v13
	v_mov_b32_e32 v185, 0
	v_lshl_add_u64 v[184:185], s[52:53], 0, v[184:185]
	v_cndmask_b32_e64 v184, v184, v182, s[42:43]
	v_cndmask_b32_e64 v185, v185, v183, s[42:43]
	global_load_dwordx4 v[92:95], v[184:185], off
	v_add_u32_e32 v186, 0xd0, v37
	v_mul_hi_i32 v187, v186, s13
	v_lshrrev_b32_e32 v188, 31, v187
	v_ashrrev_i32_e32 v187, 3, v187
	v_add_u32_e32 v187, v187, v188
	v_mad_i32_i24 v188, v187, s16, v186
	v_lshl_add_u32 v157, v187, 9, v13
	v_cmp_eq_u32_e64 s[42:43], 1, v187
	v_cmp_eq_u32_e64 s[56:57], 0, v187
	s_nop 1
	v_cndmask_b32_e64 v189, -16, -4, s[42:43]
	v_cndmask_b32_e64 v189, v189, -1, s[56:57]
	v_mad_i32_i24 v189, v189, v188, v174
	v_cmp_eq_u32_e64 s[42:43], 0, v188
	v_lshlrev_b32_e32 v184, 12, v189
	v_add_u32_e32 v184, v184, v13
	v_mov_b32_e32 v185, 0
	v_lshl_add_u64 v[184:185], s[52:53], 0, v[184:185]
	v_cndmask_b32_e64 v184, v184, v182, s[42:43]
	v_cndmask_b32_e64 v185, v185, v183, s[42:43]
	global_load_dwordx4 v[96:99], v[184:185], off
	v_add_u32_e32 v186, 0xe0, v37
	v_mul_hi_i32 v187, v186, s13
	v_lshrrev_b32_e32 v188, 31, v187
	v_ashrrev_i32_e32 v187, 3, v187
	v_add_u32_e32 v187, v187, v188
	v_mad_i32_i24 v188, v187, s16, v186
	v_lshl_add_u32 v158, v187, 9, v13
	v_cmp_eq_u32_e64 s[42:43], 1, v187
	v_cmp_eq_u32_e64 s[56:57], 0, v187
	s_nop 1
	v_cndmask_b32_e64 v189, -16, -4, s[42:43]
	v_cndmask_b32_e64 v189, v189, -1, s[56:57]
	v_mad_i32_i24 v189, v189, v188, v174
	v_cmp_eq_u32_e64 s[42:43], 0, v188
	v_lshlrev_b32_e32 v184, 12, v189
	v_add_u32_e32 v184, v184, v13
	v_mov_b32_e32 v185, 0
	v_lshl_add_u64 v[184:185], s[52:53], 0, v[184:185]
	v_cndmask_b32_e64 v184, v184, v182, s[42:43]
	v_cndmask_b32_e64 v185, v185, v183, s[42:43]
	global_load_dwordx4 v[100:103], v[184:185], off
	v_add_u32_e32 v186, 0xf0, v37
	v_mul_hi_i32 v187, v186, s13
	v_lshrrev_b32_e32 v188, 31, v187
	v_ashrrev_i32_e32 v187, 3, v187
	v_add_u32_e32 v187, v187, v188
	v_mad_i32_i24 v188, v187, s16, v186
	v_lshl_add_u32 v159, v187, 9, v13
	v_cmp_eq_u32_e64 s[42:43], 1, v187
	v_cmp_eq_u32_e64 s[56:57], 0, v187
	s_nop 1
	v_cndmask_b32_e64 v189, -16, -4, s[42:43]
	v_cndmask_b32_e64 v189, v189, -1, s[56:57]
	v_mad_i32_i24 v189, v189, v188, v174
	v_cmp_eq_u32_e64 s[42:43], 0, v188
	v_lshlrev_b32_e32 v184, 12, v189
	v_add_u32_e32 v184, v184, v13
	v_mov_b32_e32 v185, 0
	v_lshl_add_u64 v[184:185], s[52:53], 0, v[184:185]
	v_cndmask_b32_e64 v184, v184, v182, s[42:43]
	v_cndmask_b32_e64 v185, v185, v183, s[42:43]
	global_load_dwordx4 v[104:107], v[184:185], off
	v_add_u32_e32 v186, 0x100, v37
	v_mul_hi_i32 v187, v186, s13
	v_lshrrev_b32_e32 v188, 31, v187
	v_ashrrev_i32_e32 v187, 3, v187
	v_add_u32_e32 v187, v187, v188
	v_mad_i32_i24 v188, v187, s16, v186
	v_lshl_add_u32 v160, v187, 9, v13
	v_cmp_eq_u32_e64 s[42:43], 1, v187
	v_cmp_eq_u32_e64 s[56:57], 0, v187
	s_nop 1
	v_cndmask_b32_e64 v189, -16, -4, s[42:43]
	v_cndmask_b32_e64 v189, v189, -1, s[56:57]
	v_mad_i32_i24 v189, v189, v188, v174
	v_cmp_eq_u32_e64 s[42:43], 0, v188
	v_lshlrev_b32_e32 v184, 12, v189
	v_add_u32_e32 v184, v184, v13
	v_mov_b32_e32 v185, 0
	v_lshl_add_u64 v[184:185], s[52:53], 0, v[184:185]
	v_cndmask_b32_e64 v184, v184, v182, s[42:43]
	v_cndmask_b32_e64 v185, v185, v183, s[42:43]
	global_load_dwordx4 v[108:111], v[184:185], off
	v_add_u32_e32 v186, 0x110, v37
	v_mul_hi_i32 v187, v186, s13
	v_lshrrev_b32_e32 v188, 31, v187
	v_ashrrev_i32_e32 v187, 3, v187
	v_add_u32_e32 v187, v187, v188
	v_mad_i32_i24 v188, v187, s16, v186
	v_lshl_add_u32 v161, v187, 9, v13
	v_cmp_eq_u32_e64 s[42:43], 1, v187
	v_cmp_eq_u32_e64 s[56:57], 0, v187
	s_nop 1
	v_cndmask_b32_e64 v189, -16, -4, s[42:43]
	v_cndmask_b32_e64 v189, v189, -1, s[56:57]
	v_mad_i32_i24 v189, v189, v188, v174
	v_cmp_eq_u32_e64 s[42:43], 0, v188
	v_lshlrev_b32_e32 v184, 12, v189
	v_add_u32_e32 v184, v184, v13
	v_mov_b32_e32 v185, 0
	v_lshl_add_u64 v[184:185], s[52:53], 0, v[184:185]
	v_cndmask_b32_e64 v184, v184, v182, s[42:43]
	v_cndmask_b32_e64 v185, v185, v183, s[42:43]
	global_load_dwordx4 v[112:115], v[184:185], off
	v_add_u32_e32 v186, 0x120, v37
	v_mul_hi_i32 v187, v186, s13
	v_lshrrev_b32_e32 v188, 31, v187
	v_ashrrev_i32_e32 v187, 3, v187
	v_add_u32_e32 v187, v187, v188
	v_mad_i32_i24 v188, v187, s16, v186
	v_lshl_add_u32 v162, v187, 9, v13
	v_cmp_eq_u32_e64 s[42:43], 1, v187
	v_cmp_eq_u32_e64 s[56:57], 0, v187
	s_nop 1
	v_cndmask_b32_e64 v189, -16, -4, s[42:43]
	v_cndmask_b32_e64 v189, v189, -1, s[56:57]
	v_mad_i32_i24 v189, v189, v188, v174
	v_cmp_eq_u32_e64 s[42:43], 0, v188
	v_lshlrev_b32_e32 v184, 12, v189
	v_add_u32_e32 v184, v184, v13
	v_mov_b32_e32 v185, 0
	v_lshl_add_u64 v[184:185], s[52:53], 0, v[184:185]
	v_cndmask_b32_e64 v184, v184, v182, s[42:43]
	v_cndmask_b32_e64 v185, v185, v183, s[42:43]
	global_load_dwordx4 v[116:119], v[184:185], off
	v_add_u32_e32 v186, 0x130, v37
	v_mul_hi_i32 v187, v186, s13
	v_lshrrev_b32_e32 v188, 31, v187
	v_ashrrev_i32_e32 v187, 3, v187
	v_add_u32_e32 v187, v187, v188
	v_mad_i32_i24 v188, v187, s16, v186
	v_lshl_add_u32 v163, v187, 9, v13
	v_cmp_eq_u32_e64 s[42:43], 1, v187
	v_cmp_eq_u32_e64 s[56:57], 0, v187
	s_nop 1
	v_cndmask_b32_e64 v189, -16, -4, s[42:43]
	v_cndmask_b32_e64 v189, v189, -1, s[56:57]
	v_mad_i32_i24 v189, v189, v188, v174
	v_cmp_eq_u32_e64 s[42:43], 0, v188
	v_lshlrev_b32_e32 v184, 12, v189
	v_add_u32_e32 v184, v184, v13
	v_mov_b32_e32 v185, 0
	v_lshl_add_u64 v[184:185], s[52:53], 0, v[184:185]
	v_cndmask_b32_e64 v184, v184, v182, s[42:43]
	v_cndmask_b32_e64 v185, v185, v183, s[42:43]
	global_load_dwordx4 v[120:123], v[184:185], off
	v_add_u32_e32 v186, 0x140, v37
	v_mul_hi_i32 v187, v186, s13
	v_lshrrev_b32_e32 v188, 31, v187
	v_ashrrev_i32_e32 v187, 3, v187
	v_add_u32_e32 v187, v187, v188
	v_mad_i32_i24 v188, v187, s16, v186
	v_lshl_add_u32 v164, v187, 9, v13
	v_cmp_eq_u32_e64 s[42:43], 1, v187
	v_cmp_eq_u32_e64 s[56:57], 0, v187
	s_nop 1
	v_cndmask_b32_e64 v189, -16, -4, s[42:43]
	v_cndmask_b32_e64 v189, v189, -1, s[56:57]
	v_mad_i32_i24 v189, v189, v188, v174
	v_cmp_eq_u32_e64 s[42:43], 0, v188
	v_lshlrev_b32_e32 v184, 12, v189
	v_add_u32_e32 v184, v184, v13
	v_mov_b32_e32 v185, 0
	v_lshl_add_u64 v[184:185], s[52:53], 0, v[184:185]
	v_cndmask_b32_e64 v184, v184, v182, s[42:43]
	v_cndmask_b32_e64 v185, v185, v183, s[42:43]
	global_load_dwordx4 v[124:127], v[184:185], off
	v_add_u32_e32 v186, 0x150, v37
	v_mul_hi_i32 v187, v186, s13
	v_lshrrev_b32_e32 v188, 31, v187
	v_ashrrev_i32_e32 v187, 3, v187
	v_add_u32_e32 v187, v187, v188
	v_mad_i32_i24 v188, v187, s16, v186
	v_lshl_add_u32 v165, v187, 9, v13
	v_cmp_eq_u32_e64 s[42:43], 1, v187
	v_cmp_eq_u32_e64 s[56:57], 0, v187
	s_nop 1
	v_cndmask_b32_e64 v189, -16, -4, s[42:43]
	v_cndmask_b32_e64 v189, v189, -1, s[56:57]
	v_mad_i32_i24 v189, v189, v188, v174
	v_cmp_eq_u32_e64 s[42:43], 0, v188
	v_lshlrev_b32_e32 v184, 12, v189
	v_add_u32_e32 v184, v184, v13
	v_mov_b32_e32 v185, 0
	v_lshl_add_u64 v[184:185], s[52:53], 0, v[184:185]
	v_cndmask_b32_e64 v184, v184, v182, s[42:43]
	v_cndmask_b32_e64 v185, v185, v183, s[42:43]
	global_load_dwordx4 v[128:131], v[184:185], off
	v_add_u32_e32 v186, 0x160, v37
	v_mul_hi_i32 v187, v186, s13
	v_lshrrev_b32_e32 v188, 31, v187
	v_ashrrev_i32_e32 v187, 3, v187
	v_add_u32_e32 v187, v187, v188
	v_mad_i32_i24 v188, v187, s16, v186
	v_lshl_add_u32 v166, v187, 9, v13
	v_cmp_eq_u32_e64 s[42:43], 1, v187
	v_cmp_eq_u32_e64 s[56:57], 0, v187
	s_nop 1
	v_cndmask_b32_e64 v189, -16, -4, s[42:43]
	v_cndmask_b32_e64 v189, v189, -1, s[56:57]
	v_mad_i32_i24 v189, v189, v188, v174
	v_cmp_eq_u32_e64 s[42:43], 0, v188
	v_lshlrev_b32_e32 v184, 12, v189
	v_add_u32_e32 v184, v184, v13
	v_mov_b32_e32 v185, 0
	v_lshl_add_u64 v[184:185], s[52:53], 0, v[184:185]
	v_cndmask_b32_e64 v184, v184, v182, s[42:43]
	v_cndmask_b32_e64 v185, v185, v183, s[42:43]
	global_load_dwordx4 v[132:135], v[184:185], off
	v_add_u32_e32 v186, 0x170, v37
	v_mul_hi_i32 v187, v186, s13
	v_lshrrev_b32_e32 v188, 31, v187
	v_ashrrev_i32_e32 v187, 3, v187
	v_add_u32_e32 v187, v187, v188
	v_mad_i32_i24 v188, v187, s16, v186
	v_lshl_add_u32 v167, v187, 9, v13
	v_cmp_eq_u32_e64 s[42:43], 1, v187
	v_cmp_eq_u32_e64 s[56:57], 0, v187
	s_nop 1
	v_cndmask_b32_e64 v189, -16, -4, s[42:43]
	v_cndmask_b32_e64 v189, v189, -1, s[56:57]
	v_mad_i32_i24 v189, v189, v188, v174
	v_cmp_eq_u32_e64 s[42:43], 0, v188
	v_lshlrev_b32_e32 v184, 12, v189
	v_add_u32_e32 v184, v184, v13
	v_mov_b32_e32 v185, 0
	v_lshl_add_u64 v[184:185], s[52:53], 0, v[184:185]
	v_cndmask_b32_e64 v184, v184, v182, s[42:43]
	v_cndmask_b32_e64 v185, v185, v183, s[42:43]
	global_load_dwordx4 v[136:139], v[184:185], off
	v_add_u32_e32 v186, 0x180, v37
	v_cmp_gt_i32_e64 s[40:41], s21, v186
	s_nop 1
	v_cndmask_b32_e64 v186, v226, v186, s[40:41]
	v_mul_hi_i32 v187, v186, s13
	v_lshrrev_b32_e32 v188, 31, v187
	v_ashrrev_i32_e32 v187, 3, v187
	v_add_u32_e32 v187, v187, v188
	v_mad_i32_i24 v188, v187, s16, v186
	v_lshl_add_u32 v168, v187, 9, v13
	v_cmp_eq_u32_e64 s[42:43], 1, v187
	v_cmp_eq_u32_e64 s[56:57], 0, v187
	s_nop 1
	v_cndmask_b32_e64 v189, -16, -4, s[42:43]
	v_cndmask_b32_e64 v189, v189, -1, s[56:57]
	v_mad_i32_i24 v189, v189, v188, v174
	v_cmp_eq_u32_e64 s[42:43], 0, v188
	v_lshlrev_b32_e32 v184, 12, v189
	v_add_u32_e32 v184, v184, v13
	v_mov_b32_e32 v185, 0
	v_lshl_add_u64 v[184:185], s[52:53], 0, v[184:185]
	v_cndmask_b32_e64 v184, v184, v182, s[42:43]
	v_cndmask_b32_e64 v185, v185, v183, s[42:43]
	global_load_dwordx4 v[140:143], v[184:185], off
	ds_read_b128 v[196:199], v144
	ds_read_b128 v[200:203], v145
	ds_read_b128 v[204:207], v146
	ds_read_b128 v[208:211], v147
	ds_read_b128 v[212:215], v148
	s_waitcnt vmcnt(20)
	s_waitcnt lgkmcnt(0)
	v_mul_f32_e32 v216, v45, v197
	v_fmac_f32_e32 v216, v44, v196
	v_fmac_f32_e32 v216, v46, v198
	v_fmac_f32_e32 v216, v47, v199
	v_mul_f32_e32 v217, v49, v201
	v_fmac_f32_e32 v217, v48, v200
	v_fmac_f32_e32 v217, v50, v202
	v_fmac_f32_e32 v217, v51, v203
	v_mul_f32_e32 v218, v53, v205
	v_fmac_f32_e32 v218, v52, v204
	v_fmac_f32_e32 v218, v54, v206
	v_fmac_f32_e32 v218, v55, v207
	v_mul_f32_e32 v219, v57, v209
	v_fmac_f32_e32 v219, v56, v208
	v_fmac_f32_e32 v219, v58, v210
	v_fmac_f32_e32 v219, v59, v211
	v_mul_f32_e32 v220, v61, v213
	v_fmac_f32_e32 v220, v60, v212
	v_fmac_f32_e32 v220, v62, v214
	v_fmac_f32_e32 v220, v63, v215
	ds_bpermute_b32 v186, v10, v216
	ds_bpermute_b32 v187, v10, v217
	ds_bpermute_b32 v188, v10, v218
	ds_bpermute_b32 v189, v10, v219
	ds_bpermute_b32 v190, v10, v220
	s_waitcnt lgkmcnt(0)
	v_add_f32_e32 v216, v216, v186
	v_add_f32_e32 v217, v217, v187
	v_add_f32_e32 v218, v218, v188
	v_add_f32_e32 v219, v219, v189
	v_add_f32_e32 v220, v220, v190
	ds_bpermute_b32 v186, v9, v216
	ds_bpermute_b32 v187, v9, v217
	ds_bpermute_b32 v188, v9, v218
	ds_bpermute_b32 v189, v9, v219
	ds_bpermute_b32 v190, v9, v220
	s_waitcnt lgkmcnt(0)
	v_add_f32_e32 v216, v216, v186
	v_add_f32_e32 v217, v217, v187
	v_add_f32_e32 v218, v218, v188
	v_add_f32_e32 v219, v219, v189
	v_add_f32_e32 v220, v220, v190
	ds_bpermute_b32 v186, v8, v216
	ds_bpermute_b32 v187, v8, v217
	ds_bpermute_b32 v188, v8, v218
	ds_bpermute_b32 v189, v8, v219
	ds_bpermute_b32 v190, v8, v220
	s_waitcnt lgkmcnt(0)
	v_add_f32_e32 v216, v216, v186
	v_add_f32_e32 v217, v217, v187
	v_add_f32_e32 v218, v218, v188
	v_add_f32_e32 v219, v219, v189
	v_add_f32_e32 v220, v220, v190
	ds_bpermute_b32 v186, v3, v216
	ds_bpermute_b32 v187, v3, v217
	ds_bpermute_b32 v188, v3, v218
	ds_bpermute_b32 v189, v3, v219
	ds_bpermute_b32 v190, v3, v220
	s_waitcnt lgkmcnt(0)
	v_add_f32_e32 v216, v216, v186
	v_add_f32_e32 v217, v217, v187
	v_add_f32_e32 v218, v218, v188
	v_add_f32_e32 v219, v219, v189
	v_add_f32_e32 v220, v220, v190
	ds_bpermute_b32 v186, v1, v216
	ds_bpermute_b32 v187, v1, v217
	ds_bpermute_b32 v188, v1, v218
	ds_bpermute_b32 v189, v1, v219
	ds_bpermute_b32 v190, v1, v220
	s_waitcnt lgkmcnt(0)
	v_add_f32_e32 v216, v216, v186
	v_add_f32_e32 v217, v217, v187
	v_add_f32_e32 v218, v218, v188
	v_add_f32_e32 v219, v219, v189
	v_add_f32_e32 v220, v220, v190
	s_and_saveexec_b64 s[40:41], vcc
	ds_write_b32 v39, v216 offset:0
	ds_write_b32 v39, v217 offset:64
	ds_write_b32 v39, v218 offset:128
	ds_write_b32 v39, v219 offset:192
	ds_write_b32 v39, v220 offset:256
	s_or_b64 exec, exec, s[40:41]
	ds_read_b128 v[196:199], v149
	ds_read_b128 v[200:203], v150
	ds_read_b128 v[204:207], v151
	ds_read_b128 v[208:211], v152
	ds_read_b128 v[212:215], v153
	s_waitcnt vmcnt(15)
	s_waitcnt lgkmcnt(0)
	v_mul_f32_e32 v216, v65, v197
	v_fmac_f32_e32 v216, v64, v196
	v_fmac_f32_e32 v216, v66, v198
	v_fmac_f32_e32 v216, v67, v199
	v_mul_f32_e32 v217, v69, v201
	v_fmac_f32_e32 v217, v68, v200
	v_fmac_f32_e32 v217, v70, v202
	v_fmac_f32_e32 v217, v71, v203
	v_mul_f32_e32 v218, v73, v205
	v_fmac_f32_e32 v218, v72, v204
	v_fmac_f32_e32 v218, v74, v206
	v_fmac_f32_e32 v218, v75, v207
	v_mul_f32_e32 v219, v77, v209
	v_fmac_f32_e32 v219, v76, v208
	v_fmac_f32_e32 v219, v78, v210
	v_fmac_f32_e32 v219, v79, v211
	v_mul_f32_e32 v220, v81, v213
	v_fmac_f32_e32 v220, v80, v212
	v_fmac_f32_e32 v220, v82, v214
	v_fmac_f32_e32 v220, v83, v215
	ds_bpermute_b32 v186, v10, v216
	ds_bpermute_b32 v187, v10, v217
	ds_bpermute_b32 v188, v10, v218
	ds_bpermute_b32 v189, v10, v219
	ds_bpermute_b32 v190, v10, v220
	s_waitcnt lgkmcnt(0)
	v_add_f32_e32 v216, v216, v186
	v_add_f32_e32 v217, v217, v187
	v_add_f32_e32 v218, v218, v188
	v_add_f32_e32 v219, v219, v189
	v_add_f32_e32 v220, v220, v190
	ds_bpermute_b32 v186, v9, v216
	ds_bpermute_b32 v187, v9, v217
	ds_bpermute_b32 v188, v9, v218
	ds_bpermute_b32 v189, v9, v219
	ds_bpermute_b32 v190, v9, v220
	s_waitcnt lgkmcnt(0)
	v_add_f32_e32 v216, v216, v186
	v_add_f32_e32 v217, v217, v187
	v_add_f32_e32 v218, v218, v188
	v_add_f32_e32 v219, v219, v189
	v_add_f32_e32 v220, v220, v190
	ds_bpermute_b32 v186, v8, v216
	ds_bpermute_b32 v187, v8, v217
	ds_bpermute_b32 v188, v8, v218
	ds_bpermute_b32 v189, v8, v219
	ds_bpermute_b32 v190, v8, v220
	s_waitcnt lgkmcnt(0)
	v_add_f32_e32 v216, v216, v186
	v_add_f32_e32 v217, v217, v187
	v_add_f32_e32 v218, v218, v188
	v_add_f32_e32 v219, v219, v189
	v_add_f32_e32 v220, v220, v190
	ds_bpermute_b32 v186, v3, v216
	ds_bpermute_b32 v187, v3, v217
	ds_bpermute_b32 v188, v3, v218
	ds_bpermute_b32 v189, v3, v219
	ds_bpermute_b32 v190, v3, v220
	s_waitcnt lgkmcnt(0)
	v_add_f32_e32 v216, v216, v186
	v_add_f32_e32 v217, v217, v187
	v_add_f32_e32 v218, v218, v188
	v_add_f32_e32 v219, v219, v189
	v_add_f32_e32 v220, v220, v190
	ds_bpermute_b32 v186, v1, v216
	ds_bpermute_b32 v187, v1, v217
	ds_bpermute_b32 v188, v1, v218
	ds_bpermute_b32 v189, v1, v219
	ds_bpermute_b32 v190, v1, v220
	s_waitcnt lgkmcnt(0)
	v_add_f32_e32 v216, v216, v186
	v_add_f32_e32 v217, v217, v187
	v_add_f32_e32 v218, v218, v188
	v_add_f32_e32 v219, v219, v189
	v_add_f32_e32 v220, v220, v190
	s_and_saveexec_b64 s[40:41], vcc
	ds_write_b32 v39, v216 offset:320
	ds_write_b32 v39, v217 offset:384
	ds_write_b32 v39, v218 offset:448
	ds_write_b32 v39, v219 offset:512
	ds_write_b32 v39, v220 offset:576
	s_or_b64 exec, exec, s[40:41]
	ds_read_b128 v[196:199], v154
	ds_read_b128 v[200:203], v155
	ds_read_b128 v[204:207], v156
	ds_read_b128 v[208:211], v157
	ds_read_b128 v[212:215], v158
	s_waitcnt vmcnt(10)
	s_waitcnt lgkmcnt(0)
	v_mul_f32_e32 v216, v85, v197
	v_fmac_f32_e32 v216, v84, v196
	v_fmac_f32_e32 v216, v86, v198
	v_fmac_f32_e32 v216, v87, v199
	v_mul_f32_e32 v217, v89, v201
	v_fmac_f32_e32 v217, v88, v200
	v_fmac_f32_e32 v217, v90, v202
	v_fmac_f32_e32 v217, v91, v203
	v_mul_f32_e32 v218, v93, v205
	v_fmac_f32_e32 v218, v92, v204
	v_fmac_f32_e32 v218, v94, v206
	v_fmac_f32_e32 v218, v95, v207
	v_mul_f32_e32 v219, v97, v209
	v_fmac_f32_e32 v219, v96, v208
	v_fmac_f32_e32 v219, v98, v210
	v_fmac_f32_e32 v219, v99, v211
	v_mul_f32_e32 v220, v101, v213
	v_fmac_f32_e32 v220, v100, v212
	v_fmac_f32_e32 v220, v102, v214
	v_fmac_f32_e32 v220, v103, v215
	ds_bpermute_b32 v186, v10, v216
	ds_bpermute_b32 v187, v10, v217
	ds_bpermute_b32 v188, v10, v218
	ds_bpermute_b32 v189, v10, v219
	ds_bpermute_b32 v190, v10, v220
	s_waitcnt lgkmcnt(0)
	v_add_f32_e32 v216, v216, v186
	v_add_f32_e32 v217, v217, v187
	v_add_f32_e32 v218, v218, v188
	v_add_f32_e32 v219, v219, v189
	v_add_f32_e32 v220, v220, v190
	ds_bpermute_b32 v186, v9, v216
	ds_bpermute_b32 v187, v9, v217
	ds_bpermute_b32 v188, v9, v218
	ds_bpermute_b32 v189, v9, v219
	ds_bpermute_b32 v190, v9, v220
	s_waitcnt lgkmcnt(0)
	v_add_f32_e32 v216, v216, v186
	v_add_f32_e32 v217, v217, v187
	v_add_f32_e32 v218, v218, v188
	v_add_f32_e32 v219, v219, v189
	v_add_f32_e32 v220, v220, v190
	ds_bpermute_b32 v186, v8, v216
	ds_bpermute_b32 v187, v8, v217
	ds_bpermute_b32 v188, v8, v218
	ds_bpermute_b32 v189, v8, v219
	ds_bpermute_b32 v190, v8, v220
	s_waitcnt lgkmcnt(0)
	v_add_f32_e32 v216, v216, v186
	v_add_f32_e32 v217, v217, v187
	v_add_f32_e32 v218, v218, v188
	v_add_f32_e32 v219, v219, v189
	v_add_f32_e32 v220, v220, v190
	ds_bpermute_b32 v186, v3, v216
	ds_bpermute_b32 v187, v3, v217
	ds_bpermute_b32 v188, v3, v218
	ds_bpermute_b32 v189, v3, v219
	ds_bpermute_b32 v190, v3, v220
	s_waitcnt lgkmcnt(0)
	v_add_f32_e32 v216, v216, v186
	v_add_f32_e32 v217, v217, v187
	v_add_f32_e32 v218, v218, v188
	v_add_f32_e32 v219, v219, v189
	v_add_f32_e32 v220, v220, v190
	ds_bpermute_b32 v186, v1, v216
	ds_bpermute_b32 v187, v1, v217
	ds_bpermute_b32 v188, v1, v218
	ds_bpermute_b32 v189, v1, v219
	ds_bpermute_b32 v190, v1, v220
	s_waitcnt lgkmcnt(0)
	v_add_f32_e32 v216, v216, v186
	v_add_f32_e32 v217, v217, v187
	v_add_f32_e32 v218, v218, v188
	v_add_f32_e32 v219, v219, v189
	v_add_f32_e32 v220, v220, v190
	s_and_saveexec_b64 s[40:41], vcc
	ds_write_b32 v39, v216 offset:640
	ds_write_b32 v39, v217 offset:704
	ds_write_b32 v39, v218 offset:768
	ds_write_b32 v39, v219 offset:832
	ds_write_b32 v39, v220 offset:896
	s_or_b64 exec, exec, s[40:41]
	ds_read_b128 v[196:199], v159
	ds_read_b128 v[200:203], v160
	ds_read_b128 v[204:207], v161
	ds_read_b128 v[208:211], v162
	ds_read_b128 v[212:215], v163
	s_waitcnt vmcnt(5)
	s_waitcnt lgkmcnt(0)
	v_mul_f32_e32 v216, v105, v197
	v_fmac_f32_e32 v216, v104, v196
	v_fmac_f32_e32 v216, v106, v198
	v_fmac_f32_e32 v216, v107, v199
	v_mul_f32_e32 v217, v109, v201
	v_fmac_f32_e32 v217, v108, v200
	v_fmac_f32_e32 v217, v110, v202
	v_fmac_f32_e32 v217, v111, v203
	v_mul_f32_e32 v218, v113, v205
	v_fmac_f32_e32 v218, v112, v204
	v_fmac_f32_e32 v218, v114, v206
	v_fmac_f32_e32 v218, v115, v207
	v_mul_f32_e32 v219, v117, v209
	v_fmac_f32_e32 v219, v116, v208
	v_fmac_f32_e32 v219, v118, v210
	v_fmac_f32_e32 v219, v119, v211
	v_mul_f32_e32 v220, v121, v213
	v_fmac_f32_e32 v220, v120, v212
	v_fmac_f32_e32 v220, v122, v214
	v_fmac_f32_e32 v220, v123, v215
	ds_bpermute_b32 v186, v10, v216
	ds_bpermute_b32 v187, v10, v217
	ds_bpermute_b32 v188, v10, v218
	ds_bpermute_b32 v189, v10, v219
	ds_bpermute_b32 v190, v10, v220
	s_waitcnt lgkmcnt(0)
	v_add_f32_e32 v216, v216, v186
	v_add_f32_e32 v217, v217, v187
	v_add_f32_e32 v218, v218, v188
	v_add_f32_e32 v219, v219, v189
	v_add_f32_e32 v220, v220, v190
	ds_bpermute_b32 v186, v9, v216
	ds_bpermute_b32 v187, v9, v217
	ds_bpermute_b32 v188, v9, v218
	ds_bpermute_b32 v189, v9, v219
	ds_bpermute_b32 v190, v9, v220
	s_waitcnt lgkmcnt(0)
	v_add_f32_e32 v216, v216, v186
	v_add_f32_e32 v217, v217, v187
	v_add_f32_e32 v218, v218, v188
	v_add_f32_e32 v219, v219, v189
	v_add_f32_e32 v220, v220, v190
	ds_bpermute_b32 v186, v8, v216
	ds_bpermute_b32 v187, v8, v217
	ds_bpermute_b32 v188, v8, v218
	ds_bpermute_b32 v189, v8, v219
	ds_bpermute_b32 v190, v8, v220
	s_waitcnt lgkmcnt(0)
	v_add_f32_e32 v216, v216, v186
	v_add_f32_e32 v217, v217, v187
	v_add_f32_e32 v218, v218, v188
	v_add_f32_e32 v219, v219, v189
	v_add_f32_e32 v220, v220, v190
	ds_bpermute_b32 v186, v3, v216
	ds_bpermute_b32 v187, v3, v217
	ds_bpermute_b32 v188, v3, v218
	ds_bpermute_b32 v189, v3, v219
	ds_bpermute_b32 v190, v3, v220
	s_waitcnt lgkmcnt(0)
	v_add_f32_e32 v216, v216, v186
	v_add_f32_e32 v217, v217, v187
	v_add_f32_e32 v218, v218, v188
	v_add_f32_e32 v219, v219, v189
	v_add_f32_e32 v220, v220, v190
	ds_bpermute_b32 v186, v1, v216
	ds_bpermute_b32 v187, v1, v217
	ds_bpermute_b32 v188, v1, v218
	ds_bpermute_b32 v189, v1, v219
	ds_bpermute_b32 v190, v1, v220
	s_waitcnt lgkmcnt(0)
	v_add_f32_e32 v216, v216, v186
	v_add_f32_e32 v217, v217, v187
	v_add_f32_e32 v218, v218, v188
	v_add_f32_e32 v219, v219, v189
	v_add_f32_e32 v220, v220, v190
	s_and_saveexec_b64 s[40:41], vcc
	ds_write_b32 v39, v216 offset:960
	ds_write_b32 v39, v217 offset:1024
	ds_write_b32 v39, v218 offset:1088
	ds_write_b32 v39, v219 offset:1152
	ds_write_b32 v39, v220 offset:1216
	s_or_b64 exec, exec, s[40:41]
	ds_read_b128 v[196:199], v164
	ds_read_b128 v[200:203], v165
	ds_read_b128 v[204:207], v166
	ds_read_b128 v[208:211], v167
	ds_read_b128 v[212:215], v168
	s_waitcnt vmcnt(0)
	s_waitcnt lgkmcnt(0)
	v_mul_f32_e32 v216, v125, v197
	v_fmac_f32_e32 v216, v124, v196
	v_fmac_f32_e32 v216, v126, v198
	v_fmac_f32_e32 v216, v127, v199
	v_mul_f32_e32 v217, v129, v201
	v_fmac_f32_e32 v217, v128, v200
	v_fmac_f32_e32 v217, v130, v202
	v_fmac_f32_e32 v217, v131, v203
	v_mul_f32_e32 v218, v133, v205
	v_fmac_f32_e32 v218, v132, v204
	v_fmac_f32_e32 v218, v134, v206
	v_fmac_f32_e32 v218, v135, v207
	v_mul_f32_e32 v219, v137, v209
	v_fmac_f32_e32 v219, v136, v208
	v_fmac_f32_e32 v219, v138, v210
	v_fmac_f32_e32 v219, v139, v211
	v_mul_f32_e32 v220, v141, v213
	v_fmac_f32_e32 v220, v140, v212
	v_fmac_f32_e32 v220, v142, v214
	v_fmac_f32_e32 v220, v143, v215
	ds_bpermute_b32 v186, v10, v216
	ds_bpermute_b32 v187, v10, v217
	ds_bpermute_b32 v188, v10, v218
	ds_bpermute_b32 v189, v10, v219
	ds_bpermute_b32 v190, v10, v220
	s_waitcnt lgkmcnt(0)
	v_add_f32_e32 v216, v216, v186
	v_add_f32_e32 v217, v217, v187
	v_add_f32_e32 v218, v218, v188
	v_add_f32_e32 v219, v219, v189
	v_add_f32_e32 v220, v220, v190
	ds_bpermute_b32 v186, v9, v216
	ds_bpermute_b32 v187, v9, v217
	ds_bpermute_b32 v188, v9, v218
	ds_bpermute_b32 v189, v9, v219
	ds_bpermute_b32 v190, v9, v220
	s_waitcnt lgkmcnt(0)
	v_add_f32_e32 v216, v216, v186
	v_add_f32_e32 v217, v217, v187
	v_add_f32_e32 v218, v218, v188
	v_add_f32_e32 v219, v219, v189
	v_add_f32_e32 v220, v220, v190
	ds_bpermute_b32 v186, v8, v216
	ds_bpermute_b32 v187, v8, v217
	ds_bpermute_b32 v188, v8, v218
	ds_bpermute_b32 v189, v8, v219
	ds_bpermute_b32 v190, v8, v220
	s_waitcnt lgkmcnt(0)
	v_add_f32_e32 v216, v216, v186
	v_add_f32_e32 v217, v217, v187
	v_add_f32_e32 v218, v218, v188
	v_add_f32_e32 v219, v219, v189
	v_add_f32_e32 v220, v220, v190
	ds_bpermute_b32 v186, v3, v216
	ds_bpermute_b32 v187, v3, v217
	ds_bpermute_b32 v188, v3, v218
	ds_bpermute_b32 v189, v3, v219
	ds_bpermute_b32 v190, v3, v220
	s_waitcnt lgkmcnt(0)
	v_add_f32_e32 v216, v216, v186
	v_add_f32_e32 v217, v217, v187
	v_add_f32_e32 v218, v218, v188
	v_add_f32_e32 v219, v219, v189
	v_add_f32_e32 v220, v220, v190
	ds_bpermute_b32 v186, v1, v216
	ds_bpermute_b32 v187, v1, v217
	ds_bpermute_b32 v188, v1, v218
	ds_bpermute_b32 v189, v1, v219
	ds_bpermute_b32 v190, v1, v220
	s_waitcnt lgkmcnt(0)
	v_add_f32_e32 v216, v216, v186
	v_add_f32_e32 v217, v217, v187
	v_add_f32_e32 v218, v218, v188
	v_add_f32_e32 v219, v219, v189
	v_add_f32_e32 v220, v220, v190
	s_and_saveexec_b64 s[40:41], vcc
	ds_write_b32 v39, v216 offset:1280
	ds_write_b32 v39, v217 offset:1344
	ds_write_b32 v39, v218 offset:1408
	ds_write_b32 v39, v219 offset:1472
	s_or_b64 exec, exec, s[40:41]
	v_cmp_gt_u32_e64 s[42:43], 3, v37
	s_nop 3
	s_and_b64 s[42:43], s[42:43], vcc
	s_and_saveexec_b64 s[40:41], s[42:43]
	ds_write_b32 v39, v220 offset:1536
	s_or_b64 exec, exec, s[40:41]
	v_lshlrev_b32_e32 v172, 2, v0

.LBB0_1163:
	s_or_b64 exec, exec, s[4:5]
	v_cvt_f32_u32_e32 v4, v2
	s_waitcnt vmcnt(0)
	v_readfirstlane_b32 s2, v3
	v_sub_u32_e32 v3, 0, v2
	v_rcp_iflag_f32_e32 v4, v4
	v_add_u32_e32 v5, s2, v1
	v_mul_f32_e32 v4, 0x4f7ffffe, v4
	v_cvt_u32_f32_e32 v4, v4
	v_mul_lo_u32 v1, v3, v4
	v_mul_hi_u32 v1, v4, v1
	v_add_u32_e32 v1, v4, v1
	v_mul_hi_u32 v1, v5, v1
	v_mul_lo_u32 v3, v1, v2
	v_sub_u32_e32 v3, v5, v3
	v_add_u32_e32 v4, 1, v1
	v_cmp_ge_u32_e32 vcc, v3, v2
	s_nop 1
	v_cndmask_b32_e32 v1, v1, v4, vcc
	v_sub_u32_e32 v4, v3, v2
	v_cndmask_b32_e32 v3, v3, v4, vcc
	v_add_u32_e32 v4, 1, v1
	v_cmp_ge_u32_e32 vcc, v3, v2
	v_add_u32_e32 v3, 1, v5
	s_nop 0
	v_cndmask_b32_e32 v1, v1, v4, vcc
	v_mul_lo_u32 v4, v2, v1
	v_add_u32_e32 v2, v4, v2
	v_cmp_ne_u32_e32 vcc, v3, v2
	s_and_saveexec_b64 s[4:5], vcc
	s_xor_b64 s[4:5], exec, s[4:5]
	s_cbranch_execz .LBB0_1177
	v_readlane_b32 s6, v255, 19
	v_readlane_b32 s7, v255, 20
	s_waitcnt lgkmcnt(0)
	s_nop 3
	global_load_dword v0, v173, s[6:7] sc1
	s_waitcnt vmcnt(0)
	v_cmp_eq_u32_e32 vcc, v0, v1
	s_and_saveexec_b64 s[6:7], vcc
	s_cbranch_execz .LBB0_1176
	s_mov_b32 s2, 1
	s_mov_b64 s[8:9], 0
	s_branch .LBB0_1167

.LBB0_1171:
	v_readlane_b32 s26, v255, 19
	v_readlane_b32 s27, v255, 20
	s_add_i32 s2, s2, 1
	s_mov_b64 s[28:29], -1
	s_nop 2
	global_load_dword v0, v173, s[26:27] sc1
	s_waitcnt vmcnt(0)
	v_cmp_ne_u32_e32 vcc, v0, v1
	s_orn2_b64 s[26:27], vcc, exec
	s_branch .LBB0_1166

.LBB0_1195:
	s_or_b64 exec, exec, s[4:5]
	s_mov_b64 s[4:5], exec
	v_mbcnt_lo_u32_b32 v0, s4, 0
	v_mbcnt_hi_u32_b32 v0, s5, v0
	v_cmp_eq_u32_e32 vcc, 0, v0
	s_waitcnt vmcnt(0)
	buffer_inv sc1
	s_waitcnt vmcnt(0)
